# row sums via v_pk_add_f32; lambda computed once per phase instead of per attention unit
# speedup vs baseline: 1.0017x; 1.0017x over previous
; template <int VAR>
; __device__ __forceinline__ void attn_unit(const Args& a, int l, int b, int h, int qrow0  , bool ctxu, const bf16* Z, bf16* Y, LAS unsigned char* lds) {
;     ...
;     float lam, omli;
;     { float s1 = 0.f, s2 = 0.f;
;       for (int i = 0; i < 32; ++i) { s1 += a.lam_q1[l * 32 + i] * a.lam_k1[l * 32 + i]; s2 += a.lam_q2[l * 32 + i] * a.lam_k2[l * 32 + i]; }
;       const float li = 0.8f - 0.6f * expf(-0.3f * (float)l); lam = expf(s1) - expf(s2) + li; omli = 1.f - li; }
.LBB0_426:
	v_readlane_b32 s8, v254, 46
	v_readlane_b32 s9, v254, 47
	s_andn2_b64 vcc, exec, s[8:9]
	s_cbranch_vccnz .LBB0_464
	v_cvt_f32_u32_e32 v0, s68
	s_mov_b32 s8, 0x3fb8aa3b
	s_lshl_b32 s72, s68, 5
	v_readlane_b32 s36, v252, 27
	v_mul_f32_e32 v0, 0xbe99999a, v0
	v_mul_f32_e32 v1, 0x3fb8aa3b, v0
	v_fma_f32 v2, v0, s8, -v1
	v_rndne_f32_e32 v3, v1
	v_fmac_f32_e32 v2, 0x32a5705f, v0
	v_sub_f32_e32 v1, v1, v3
	v_add_f32_e32 v1, v1, v2
	v_cvt_i32_f32_e32 v3, v3
	v_exp_f32_e32 v1, v1
	s_mov_b32 s8, 0xc2ce8ed0
	v_cmp_ngt_f32_e32 vcc, s8, v0
	s_mov_b32 s8, 0x42b17218
	v_ldexp_f32 v1, v1, v3
	v_cndmask_b32_e32 v1, 0, v1, vcc
	v_cmp_nlt_f32_e32 vcc, s8, v0
	s_lshl_b64 s[8:9], s[72:73], 2
	v_readlane_b32 s40, v252, 31
	v_readlane_b32 s46, v252, 37
	v_readlane_b32 s41, v252, 32
	v_readlane_b32 s47, v252, 38
	s_add_u32 s40, s46, s8
	v_readlane_b32 s42, v252, 33
	v_readlane_b32 s48, v252, 39
	s_addc_u32 s41, s47, s9
	v_readlane_b32 s43, v252, 34
	v_readlane_b32 s49, v252, 40
	s_add_u32 s42, s48, s8
	v_readlane_b32 s44, v252, 35
	v_readlane_b32 s50, v252, 41
	s_addc_u32 s43, s49, s9
	v_readlane_b32 s45, v252, 36
	v_readlane_b32 s51, v252, 42
	s_add_u32 s44, s50, s8
	v_cndmask_b32_e32 v0, v245, v1, vcc
	s_addc_u32 s45, s51, s9
	v_readlane_b32 s76, v252, 43
	v_fmamk_f32 v221, v0, 0xbf19999a, v220
	v_readlane_b32 s77, v252, 44
	s_add_u32 s46, s76, s8
	v_sub_f32_e32 v226, 1.0, v221
	s_addc_u32 s47, s77, s9
	s_lshl_b32 s58, s68, 6
	s_mov_b32 s59, 0
	global_load_dwordx4 v[0:3], v217, s[40:41]
	global_load_dwordx4 v[4:7], v217, s[40:41] offset:16
	global_load_dwordx4 v[8:11], v217, s[40:41] offset:32
	global_load_dwordx4 v[12:15], v217, s[40:41] offset:48
	global_load_dwordx4 v[16:19], v217, s[40:41] offset:64
	global_load_dwordx4 v[20:23], v217, s[40:41] offset:80
	global_load_dwordx4 v[24:27], v217, s[40:41] offset:96
	global_load_dwordx4 v[28:31], v217, s[40:41] offset:112
	global_load_dwordx4 v[32:35], v217, s[42:43]
	global_load_dwordx4 v[36:39], v217, s[42:43] offset:16
	global_load_dwordx4 v[40:43], v217, s[42:43] offset:32
	global_load_dwordx4 v[44:47], v217, s[42:43] offset:48
	global_load_dwordx4 v[48:51], v217, s[42:43] offset:64
	global_load_dwordx4 v[52:55], v217, s[42:43] offset:80
	global_load_dwordx4 v[56:59], v217, s[42:43] offset:96
	global_load_dwordx4 v[60:63], v217, s[42:43] offset:112
	global_load_dwordx4 v[64:67], v217, s[44:45]
	global_load_dwordx4 v[68:71], v217, s[44:45] offset:16
	global_load_dwordx4 v[72:75], v217, s[44:45] offset:32
	global_load_dwordx4 v[76:79], v217, s[44:45] offset:48
	global_load_dwordx4 v[80:83], v217, s[44:45] offset:64
	global_load_dwordx4 v[84:87], v217, s[44:45] offset:80
	global_load_dwordx4 v[88:91], v217, s[44:45] offset:96
	global_load_dwordx4 v[92:95], v217, s[44:45] offset:112
	global_load_dwordx4 v[96:99], v217, s[46:47]
	global_load_dwordx4 v[100:103], v217, s[46:47] offset:16
	global_load_dwordx4 v[104:107], v217, s[46:47] offset:32
	global_load_dwordx4 v[108:111], v217, s[46:47] offset:48
	global_load_dwordx4 v[112:115], v217, s[46:47] offset:64
	global_load_dwordx4 v[116:119], v217, s[46:47] offset:80
	global_load_dwordx4 v[120:123], v217, s[46:47] offset:96
	global_load_dwordx4 v[124:127], v217, s[46:47] offset:112
	s_mov_b32 s50, 0x3fb8aa3b
	s_mov_b32 s51, 0xc2ce8ed0
	s_mov_b32 s93, 0x42b17218
	s_waitcnt vmcnt(0)
	v_fma_f32 v128, v0, v32, 0
	v_fmac_f32_e32 v128, v1, v33
	v_fmac_f32_e32 v128, v2, v34
	v_fmac_f32_e32 v128, v3, v35
	v_fmac_f32_e32 v128, v4, v36
	v_fmac_f32_e32 v128, v5, v37
	v_fmac_f32_e32 v128, v6, v38
	v_fmac_f32_e32 v128, v7, v39
	v_fmac_f32_e32 v128, v8, v40
	v_fmac_f32_e32 v128, v9, v41
	v_fmac_f32_e32 v128, v10, v42
	v_fmac_f32_e32 v128, v11, v43
	v_fmac_f32_e32 v128, v12, v44
	v_fmac_f32_e32 v128, v13, v45
	v_fmac_f32_e32 v128, v14, v46
	v_fmac_f32_e32 v128, v15, v47
	v_fmac_f32_e32 v128, v16, v48
	v_fmac_f32_e32 v128, v17, v49
	v_fmac_f32_e32 v128, v18, v50
	v_fmac_f32_e32 v128, v19, v51
	v_fmac_f32_e32 v128, v20, v52
	v_fmac_f32_e32 v128, v21, v53
	v_fmac_f32_e32 v128, v22, v54
	v_fmac_f32_e32 v128, v23, v55
	v_fmac_f32_e32 v128, v24, v56
	v_fmac_f32_e32 v128, v25, v57
	v_fmac_f32_e32 v128, v26, v58
	v_fmac_f32_e32 v128, v27, v59
	v_fmac_f32_e32 v128, v28, v60
	v_fmac_f32_e32 v128, v29, v61
	v_fmac_f32_e32 v128, v30, v62
	v_fmac_f32_e32 v128, v31, v63
	v_fma_f32 v129, v64, v96, 0
	v_fmac_f32_e32 v129, v65, v97
	v_fmac_f32_e32 v129, v66, v98
	v_fmac_f32_e32 v129, v67, v99
	v_fmac_f32_e32 v129, v68, v100
	v_fmac_f32_e32 v129, v69, v101
	v_fmac_f32_e32 v129, v70, v102
	v_fmac_f32_e32 v129, v71, v103
	v_fmac_f32_e32 v129, v72, v104
	v_fmac_f32_e32 v129, v73, v105
	v_fmac_f32_e32 v129, v74, v106
	v_fmac_f32_e32 v129, v75, v107
	v_fmac_f32_e32 v129, v76, v108
	v_fmac_f32_e32 v129, v77, v109
	v_fmac_f32_e32 v129, v78, v110
	v_fmac_f32_e32 v129, v79, v111
	v_fmac_f32_e32 v129, v80, v112
	v_fmac_f32_e32 v129, v81, v113
	v_fmac_f32_e32 v129, v82, v114
	v_fmac_f32_e32 v129, v83, v115
	v_fmac_f32_e32 v129, v84, v116
	v_fmac_f32_e32 v129, v85, v117
	v_fmac_f32_e32 v129, v86, v118
	v_fmac_f32_e32 v129, v87, v119
	v_fmac_f32_e32 v129, v88, v120
	v_fmac_f32_e32 v129, v89, v121
	v_fmac_f32_e32 v129, v90, v122
	v_fmac_f32_e32 v129, v91, v123
	v_fmac_f32_e32 v129, v92, v124
	v_fmac_f32_e32 v129, v93, v125
	v_fmac_f32_e32 v129, v94, v126
	v_fmac_f32_e32 v129, v95, v127
	v_mul_f32_e32 v132, 0x3fb8aa3b, v128
	v_fma_f32 v133, v128, s50, -v132
	v_rndne_f32_e32 v134, v132
	v_fmac_f32_e32 v133, 0x32a5705f, v128
	v_sub_f32_e32 v132, v132, v134
	v_add_f32_e32 v132, v132, v133
	v_exp_f32_e32 v132, v132
	v_cvt_i32_f32_e32 v133, v134
	v_cmp_ngt_f32_e32 vcc, s51, v128
	v_ldexp_f32 v132, v132, v133
	s_nop 1
	v_cndmask_b32_e32 v132, 0, v132, vcc
	v_cmp_nlt_f32_e32 vcc, s93, v128
	s_nop 1
	v_cndmask_b32_e32 v130, v245, v132, vcc
	v_mul_f32_e32 v132, 0x3fb8aa3b, v129
	v_fma_f32 v133, v129, s50, -v132
	v_rndne_f32_e32 v134, v132
	v_fmac_f32_e32 v133, 0x32a5705f, v129
	v_sub_f32_e32 v132, v132, v134
	v_add_f32_e32 v132, v132, v133
	v_exp_f32_e32 v132, v132
	v_cvt_i32_f32_e32 v133, v134
	v_cmp_ngt_f32_e32 vcc, s51, v129
	v_ldexp_f32 v132, v132, v133
	s_nop 1
	v_cndmask_b32_e32 v132, 0, v132, vcc
	v_cmp_nlt_f32_e32 vcc, s93, v129
	s_nop 1
	v_cndmask_b32_e32 v131, v245, v132, vcc
	v_sub_f32_e32 v130, v130, v131
	v_add_f32_e32 v202, v221, v130
	v_readlane_b32 s8, v254, 44
	v_readlane_b32 s37, v252, 28
	v_readlane_b32 s38, v252, 29
	v_readlane_b32 s39, v252, 30
	v_readlane_b32 s78, v252, 45
	v_readlane_b32 s79, v252, 46
	v_readlane_b32 s80, v252, 47
	v_readlane_b32 s81, v252, 48
	v_readlane_b32 s82, v252, 49
	v_readlane_b32 s83, v252, 50
	v_readlane_b32 s84, v252, 51
	v_readlane_b32 s85, v252, 52
	v_readlane_b32 s86, v252, 53
	v_readlane_b32 s87, v252, 54
	v_readlane_b32 s88, v252, 55
	v_readlane_b32 s89, v252, 56
	v_readlane_b32 s90, v252, 57
	v_readlane_b32 s91, v252, 58
	s_branch .LBB0_429

.Lat_back0:
	v_exp_f32_e32 v96, v96
	v_exp_f32_e32 v97, v97
	v_exp_f32_e32 v98, v98
	v_exp_f32_e32 v99, v99
	v_exp_f32_e32 v100, v100
	v_exp_f32_e32 v101, v101
	v_exp_f32_e32 v102, v102
	v_exp_f32_e32 v103, v103
	v_cvt_pk_bf16_f32 v40, v96, v97
	v_cvt_pk_bf16_f32 v41, v98, v99
	v_cvt_pk_bf16_f32 v42, v100, v101
	v_cvt_pk_bf16_f32 v43, v102, v103
	v_pk_add_f32 v[32:33], v[32:33], v[96:97]
	v_pk_add_f32 v[32:33], v[32:33], v[98:99]
	v_pk_add_f32 v[32:33], v[32:33], v[100:101]
	v_pk_add_f32 v[32:33], v[32:33], v[102:103]
	s_waitcnt lgkmcnt(15)
	v_mfma_f32_32x32x16_bf16 v[0:15], v[40:43], v[168:171], v[0:15]
	v_exp_f32_e32 v104, v104
	v_exp_f32_e32 v105, v105
	v_exp_f32_e32 v106, v106
	v_exp_f32_e32 v107, v107
	v_mfma_f32_32x32x16_bf16 v[16:31], v[40:43], v[172:175], v[16:31]
	v_exp_f32_e32 v108, v108
	v_exp_f32_e32 v109, v109
	v_exp_f32_e32 v110, v110
	v_exp_f32_e32 v111, v111
	v_cvt_pk_bf16_f32 v44, v104, v105
	v_cvt_pk_bf16_f32 v45, v106, v107
	v_cvt_pk_bf16_f32 v46, v108, v109
	v_cvt_pk_bf16_f32 v47, v110, v111
	v_pk_add_f32 v[32:33], v[32:33], v[104:105]
	v_pk_add_f32 v[32:33], v[32:33], v[106:107]
	v_pk_add_f32 v[32:33], v[32:33], v[108:109]
	v_pk_add_f32 v[32:33], v[32:33], v[110:111]
	s_waitcnt lgkmcnt(12)
	v_mfma_f32_32x32x16_bf16 v[0:15], v[44:47], v[176:179], v[0:15]
	v_exp_f32_e32 v112, v112
	v_exp_f32_e32 v113, v113
	v_exp_f32_e32 v114, v114
	v_exp_f32_e32 v115, v115
	v_mfma_f32_32x32x16_bf16 v[16:31], v[44:47], v[180:183], v[16:31]
	v_exp_f32_e32 v116, v116
	v_exp_f32_e32 v117, v117
	v_exp_f32_e32 v118, v118
	v_exp_f32_e32 v119, v119
	v_cvt_pk_bf16_f32 v40, v112, v113
	v_cvt_pk_bf16_f32 v41, v114, v115
	v_cvt_pk_bf16_f32 v42, v116, v117
	v_cvt_pk_bf16_f32 v43, v118, v119
	v_pk_add_f32 v[32:33], v[32:33], v[112:113]
	v_pk_add_f32 v[32:33], v[32:33], v[114:115]
	v_pk_add_f32 v[32:33], v[32:33], v[116:117]
	v_pk_add_f32 v[32:33], v[32:33], v[118:119]
	s_waitcnt lgkmcnt(8)
	v_mfma_f32_32x32x16_bf16 v[0:15], v[40:43], v[184:187], v[0:15]
	v_exp_f32_e32 v120, v120
	v_exp_f32_e32 v121, v121
	v_exp_f32_e32 v122, v122
	v_exp_f32_e32 v123, v123
	v_mfma_f32_32x32x16_bf16 v[16:31], v[40:43], v[188:191], v[16:31]
	v_exp_f32_e32 v124, v124
	v_exp_f32_e32 v125, v125
	v_exp_f32_e32 v126, v126
	v_exp_f32_e32 v127, v127
	v_cvt_pk_bf16_f32 v44, v120, v121
	v_cvt_pk_bf16_f32 v45, v122, v123
	v_cvt_pk_bf16_f32 v46, v124, v125
	v_cvt_pk_bf16_f32 v47, v126, v127
	v_pk_add_f32 v[32:33], v[32:33], v[120:121]
	v_pk_add_f32 v[32:33], v[32:33], v[122:123]
	v_pk_add_f32 v[32:33], v[32:33], v[124:125]
	v_pk_add_f32 v[32:33], v[32:33], v[126:127]
	s_waitcnt lgkmcnt(4)
	v_mfma_f32_32x32x16_bf16 v[0:15], v[44:47], v[192:195], v[0:15]
	v_mfma_f32_32x32x16_bf16 v[16:31], v[44:47], v[196:199], v[16:31]
	s_waitcnt lgkmcnt(0)
	v_mfma_f32_32x32x16_bf16 v[96:111], v[80:83], v[136:139], v[64:79]
	ds_read_b64_tr_b16 v[168:169], v249 offset:8192
	ds_read_b64_tr_b16 v[170:171], v249 offset:9216
	ds_read_b64_tr_b16 v[172:173], v249 offset:8704
	ds_read_b64_tr_b16 v[174:175], v249 offset:9728
	v_mfma_f32_32x32x16_bf16 v[96:111], v[84:87], v[140:143], v[96:111]
	ds_read_b64_tr_b16 v[176:177], v249 offset:10240
	ds_read_b64_tr_b16 v[178:179], v249 offset:11264
	ds_read_b64_tr_b16 v[180:181], v249 offset:10752
	ds_read_b64_tr_b16 v[182:183], v249 offset:11776
	v_mfma_f32_32x32x16_bf16 v[112:127], v[88:91], v[136:139], v[64:79]
	ds_read_b64_tr_b16 v[184:185], v249 offset:12288
	ds_read_b64_tr_b16 v[186:187], v249 offset:13312
	ds_read_b64_tr_b16 v[188:189], v249 offset:12800
	ds_read_b64_tr_b16 v[190:191], v249 offset:13824
	v_mfma_f32_32x32x16_bf16 v[112:127], v[92:95], v[140:143], v[112:127]
	ds_read_b64_tr_b16 v[192:193], v249 offset:14336
	ds_read_b64_tr_b16 v[194:195], v249 offset:15360
	ds_read_b64_tr_b16 v[196:197], v249 offset:14848
	ds_read_b64_tr_b16 v[198:199], v249 offset:15872
	v_max3_f32 v34, v96, v97, v98
	v_max3_f32 v35, v99, v100, v101
	v_max3_f32 v34, v34, v102, v103
	v_max3_f32 v35, v35, v104, v105
	v_max3_f32 v34, v34, v106, v107
	v_max3_f32 v35, v35, v108, v109
	v_max3_f32 v34, v34, v110, v111
	s_nop 1
	v_max3_f32 v35, v35, v112, v113
	v_max3_f32 v34, v34, v114, v115
	v_max3_f32 v35, v35, v116, v117
	v_max3_f32 v34, v34, v118, v119
	v_max3_f32 v35, v35, v120, v121
	v_max3_f32 v34, v34, v122, v123
	v_max3_f32 v35, v35, v124, v125
	v_max3_f32 v34, v34, v126, v127
	v_max_f32_e32 v34, v34, v35
	v_mov_b32_e32 v35, v34
	s_nop 1
	v_permlane32_swap_b32_e32 v34, v35
	v_max_f32_e32 v34, v34, v35
	v_cmp_lt_f32_e32 vcc, s4, v34
	s_cbranch_vccnz .Lat_rare1
; #define AT_LOAD(K0, K1, V0, V1, T) do { const size_t e_ = (size_t)(128 * (T) + sr) * 64 + sc; \
;         K0 = *(const bf16x8*)(kcp + e_); V0 = *(const bf16x8*)(vcp + e_); K1 = *(const bf16x8*)(kcp + e_ + 64 * 64); V1 = *(const bf16x8*)(vcp + e_ + 64 * 64); } while (0)
; #define AT_STORE(K0, K1, V0, V1, BUF) do { *(LAS bf16x8*)(lds + AT_K + (BUF) * AT_KB + kst0) = K0; *(LAS bf16x8*)(lds + AT_K + (BUF) * AT_KB + kst1) = K1; \
;         *(LAS bf16x8*)(lds + AT_V + (BUF) * AT_VB + vst0) = V0; *(LAS bf16x8*)(lds + AT_V + (BUF) * AT_VB + vst1) = V1; } while (0)
; template <int VAR>
; __device__ __forceinline__ void attn_unit(const Args& a, int l, int b, int h, int qrow0  , bool ctxu, const bf16* Z, bf16* Y, LAS unsigned char* lds) {
;     ...
;         __syncthreads();
;         if (t + 2 < NT) AT_LOAD(ka0, ka1, va0, va1, t + 2);
;         attn_tile(Kb0, vb0, q0, q1, negm, m, o0, o1, lacc, t == 0, wsf, r32, hi);
;         AT_STORE(kb0, kb1, vb0_, vb1_, 1);
;         __syncthreads();
;         if (t + 3 < NT) AT_LOAD(kb0, kb1, vb0_, vb1_, t + 3);
;         attn_tile(Kb0 + AT_KB, vb0 + AT_VB, q0, q1, negm, m, o0, o1, lacc, false, wsf, r32, hi);
;         if (t + 2 < NT) AT_STORE(ka0, ka1, va0, va1, 0);
.Lat_back1:
	s_waitcnt vmcnt(4)
	ds_write_b128 v250, v[152:155] offset:18432
	ds_write_b128 v250, v[160:163] offset:27648
	ds_write_b128 v251, v[156:159] offset:53248
	ds_write_b128 v229, v[164:167] offset:53248
	v_exp_f32_e32 v96, v96
	v_exp_f32_e32 v97, v97
	v_exp_f32_e32 v98, v98
	v_exp_f32_e32 v99, v99
	v_exp_f32_e32 v100, v100
	v_exp_f32_e32 v101, v101
	v_exp_f32_e32 v102, v102
	v_exp_f32_e32 v103, v103
	v_cvt_pk_bf16_f32 v40, v96, v97
	v_cvt_pk_bf16_f32 v41, v98, v99
	v_cvt_pk_bf16_f32 v42, v100, v101
	v_cvt_pk_bf16_f32 v43, v102, v103
	v_pk_add_f32 v[32:33], v[32:33], v[96:97]
	v_pk_add_f32 v[32:33], v[32:33], v[98:99]
	v_pk_add_f32 v[32:33], v[32:33], v[100:101]
	v_pk_add_f32 v[32:33], v[32:33], v[102:103]
	s_waitcnt lgkmcnt(15)
	v_mfma_f32_32x32x16_bf16 v[0:15], v[40:43], v[168:171], v[0:15]
	v_exp_f32_e32 v104, v104
	v_exp_f32_e32 v105, v105
	v_exp_f32_e32 v106, v106
	v_exp_f32_e32 v107, v107
	v_mfma_f32_32x32x16_bf16 v[16:31], v[40:43], v[172:175], v[16:31]
	v_exp_f32_e32 v108, v108
	v_exp_f32_e32 v109, v109
	v_exp_f32_e32 v110, v110
	v_exp_f32_e32 v111, v111
	v_cvt_pk_bf16_f32 v44, v104, v105
	v_cvt_pk_bf16_f32 v45, v106, v107
	v_cvt_pk_bf16_f32 v46, v108, v109
	v_cvt_pk_bf16_f32 v47, v110, v111
	v_pk_add_f32 v[32:33], v[32:33], v[104:105]
	v_pk_add_f32 v[32:33], v[32:33], v[106:107]
	v_pk_add_f32 v[32:33], v[32:33], v[108:109]
	v_pk_add_f32 v[32:33], v[32:33], v[110:111]
	s_waitcnt lgkmcnt(12)
	v_mfma_f32_32x32x16_bf16 v[0:15], v[44:47], v[176:179], v[0:15]
	v_exp_f32_e32 v112, v112
	v_exp_f32_e32 v113, v113
	v_exp_f32_e32 v114, v114
	v_exp_f32_e32 v115, v115
	v_mfma_f32_32x32x16_bf16 v[16:31], v[44:47], v[180:183], v[16:31]
	v_exp_f32_e32 v116, v116
	v_exp_f32_e32 v117, v117
	v_exp_f32_e32 v118, v118
	v_exp_f32_e32 v119, v119
	v_cvt_pk_bf16_f32 v40, v112, v113
	v_cvt_pk_bf16_f32 v41, v114, v115
	v_cvt_pk_bf16_f32 v42, v116, v117
	v_cvt_pk_bf16_f32 v43, v118, v119
	v_pk_add_f32 v[32:33], v[32:33], v[112:113]
	v_pk_add_f32 v[32:33], v[32:33], v[114:115]
	v_pk_add_f32 v[32:33], v[32:33], v[116:117]
	v_pk_add_f32 v[32:33], v[32:33], v[118:119]
	s_waitcnt lgkmcnt(0)
	s_barrier
	global_load_dwordx4 v[152:155], v200, s[36:37]
	global_load_dwordx4 v[156:159], v200, s[48:49]
	global_load_dwordx4 v[160:163], v201, s[36:37]
	global_load_dwordx4 v[164:167], v201, s[48:49]
	s_cmp_lt_u32 s93, 65
	s_cselect_b32 s50, 0x4000, 0
	s_add_u32 s36, s36, s50
	s_addc_u32 s37, s37, 0
	s_add_u32 s48, s48, s50
	s_addc_u32 s49, s49, 0
	s_add_u32 s93, s93, 1
	ds_read_b128 v[48:51], v235 offset:18432
	ds_read_b128 v[52:55], v235 offset:18464
	ds_read_b128 v[56:59], v235 offset:23040
	ds_read_b128 v[60:63], v235 offset:23072
	v_mfma_f32_32x32x16_bf16 v[0:15], v[40:43], v[184:187], v[0:15]
	v_exp_f32_e32 v120, v120
	v_exp_f32_e32 v121, v121
	v_exp_f32_e32 v122, v122
	v_exp_f32_e32 v123, v123
	v_mfma_f32_32x32x16_bf16 v[16:31], v[40:43], v[188:191], v[16:31]
	v_exp_f32_e32 v124, v124
	v_exp_f32_e32 v125, v125
	v_exp_f32_e32 v126, v126
	v_exp_f32_e32 v127, v127
	v_cvt_pk_bf16_f32 v44, v120, v121
	v_cvt_pk_bf16_f32 v45, v122, v123
	v_cvt_pk_bf16_f32 v46, v124, v125
	v_cvt_pk_bf16_f32 v47, v126, v127
	v_pk_add_f32 v[32:33], v[32:33], v[120:121]
	v_pk_add_f32 v[32:33], v[32:33], v[122:123]
	v_pk_add_f32 v[32:33], v[32:33], v[124:125]
	v_pk_add_f32 v[32:33], v[32:33], v[126:127]
	v_mfma_f32_32x32x16_bf16 v[0:15], v[44:47], v[192:195], v[0:15]
	v_mfma_f32_32x32x16_bf16 v[16:31], v[44:47], v[196:199], v[16:31]
	s_waitcnt lgkmcnt(0)
	v_mfma_f32_32x32x16_bf16 v[96:111], v[48:51], v[136:139], v[64:79]
	ds_read_b64_tr_b16 v[168:169], v233 offset:0
	ds_read_b64_tr_b16 v[170:171], v233 offset:1024
	ds_read_b64_tr_b16 v[172:173], v233 offset:512
	ds_read_b64_tr_b16 v[174:175], v233 offset:1536
	v_mfma_f32_32x32x16_bf16 v[96:111], v[52:55], v[140:143], v[96:111]
	ds_read_b64_tr_b16 v[176:177], v233 offset:2048
	ds_read_b64_tr_b16 v[178:179], v233 offset:3072
	ds_read_b64_tr_b16 v[180:181], v233 offset:2560
	ds_read_b64_tr_b16 v[182:183], v233 offset:3584
	v_mfma_f32_32x32x16_bf16 v[112:127], v[56:59], v[136:139], v[64:79]
	ds_read_b64_tr_b16 v[184:185], v233 offset:4096
	ds_read_b64_tr_b16 v[186:187], v233 offset:5120
	ds_read_b64_tr_b16 v[188:189], v233 offset:4608
	ds_read_b64_tr_b16 v[190:191], v233 offset:5632
	v_mfma_f32_32x32x16_bf16 v[112:127], v[60:63], v[140:143], v[112:127]
	ds_read_b64_tr_b16 v[192:193], v233 offset:6144
	ds_read_b64_tr_b16 v[194:195], v233 offset:7168
	ds_read_b64_tr_b16 v[196:197], v233 offset:6656
	ds_read_b64_tr_b16 v[198:199], v233 offset:7680
	ds_read_b128 v[80:83], v235 offset:27648
	ds_read_b128 v[84:87], v235 offset:27680
	ds_read_b128 v[88:91], v235 offset:32256
	ds_read_b128 v[92:95], v235 offset:32288
	v_max3_f32 v34, v96, v97, v98
	v_max3_f32 v35, v99, v100, v101
	v_max3_f32 v34, v34, v102, v103
	v_max3_f32 v35, v35, v104, v105
	v_max3_f32 v34, v34, v106, v107
	v_max3_f32 v35, v35, v108, v109
	v_max3_f32 v34, v34, v110, v111
	v_max3_f32 v35, v35, v112, v113
	v_max3_f32 v34, v34, v114, v115
	v_max3_f32 v35, v35, v116, v117
	v_max3_f32 v34, v34, v118, v119
	v_max3_f32 v35, v35, v120, v121
	v_max3_f32 v34, v34, v122, v123
	v_max3_f32 v35, v35, v124, v125
	v_max3_f32 v34, v34, v126, v127
	v_max_f32_e32 v34, v34, v35
	v_mov_b32_e32 v35, v34
	s_nop 1
	v_permlane32_swap_b32_e32 v34, v35
	v_max_f32_e32 v34, v34, v35
	v_cmp_lt_f32_e32 vcc, s4, v34
	s_cbranch_vccnz .Lat_rare2
.Lat_back2:
	v_exp_f32_e32 v96, v96
	v_exp_f32_e32 v97, v97
	v_exp_f32_e32 v98, v98
	v_exp_f32_e32 v99, v99
	v_exp_f32_e32 v100, v100
	v_exp_f32_e32 v101, v101
	v_exp_f32_e32 v102, v102
	v_exp_f32_e32 v103, v103
	v_cvt_pk_bf16_f32 v40, v96, v97
	v_cvt_pk_bf16_f32 v41, v98, v99
	v_cvt_pk_bf16_f32 v42, v100, v101
	v_cvt_pk_bf16_f32 v43, v102, v103
	v_pk_add_f32 v[32:33], v[32:33], v[96:97]
	v_pk_add_f32 v[32:33], v[32:33], v[98:99]
	v_pk_add_f32 v[32:33], v[32:33], v[100:101]
	v_pk_add_f32 v[32:33], v[32:33], v[102:103]
	s_waitcnt lgkmcnt(15)
	v_mfma_f32_32x32x16_bf16 v[0:15], v[40:43], v[168:171], v[0:15]
	v_exp_f32_e32 v104, v104
	v_exp_f32_e32 v105, v105
	v_exp_f32_e32 v106, v106
	v_exp_f32_e32 v107, v107
	v_mfma_f32_32x32x16_bf16 v[16:31], v[40:43], v[172:175], v[16:31]
	v_exp_f32_e32 v108, v108
	v_exp_f32_e32 v109, v109
	v_exp_f32_e32 v110, v110
	v_exp_f32_e32 v111, v111
	v_cvt_pk_bf16_f32 v44, v104, v105
	v_cvt_pk_bf16_f32 v45, v106, v107
	v_cvt_pk_bf16_f32 v46, v108, v109
	v_cvt_pk_bf16_f32 v47, v110, v111
	v_pk_add_f32 v[32:33], v[32:33], v[104:105]
	v_pk_add_f32 v[32:33], v[32:33], v[106:107]
	v_pk_add_f32 v[32:33], v[32:33], v[108:109]
	v_pk_add_f32 v[32:33], v[32:33], v[110:111]
	s_waitcnt lgkmcnt(12)
	v_mfma_f32_32x32x16_bf16 v[0:15], v[44:47], v[176:179], v[0:15]
	v_exp_f32_e32 v112, v112
	v_exp_f32_e32 v113, v113
	v_exp_f32_e32 v114, v114
	v_exp_f32_e32 v115, v115
	v_mfma_f32_32x32x16_bf16 v[16:31], v[44:47], v[180:183], v[16:31]
	v_exp_f32_e32 v116, v116
	v_exp_f32_e32 v117, v117
	v_exp_f32_e32 v118, v118
	v_exp_f32_e32 v119, v119
	v_cvt_pk_bf16_f32 v40, v112, v113
	v_cvt_pk_bf16_f32 v41, v114, v115
	v_cvt_pk_bf16_f32 v42, v116, v117
	v_cvt_pk_bf16_f32 v43, v118, v119
	v_pk_add_f32 v[32:33], v[32:33], v[112:113]
	v_pk_add_f32 v[32:33], v[32:33], v[114:115]
	v_pk_add_f32 v[32:33], v[32:33], v[116:117]
	v_pk_add_f32 v[32:33], v[32:33], v[118:119]
	s_waitcnt lgkmcnt(8)
	v_mfma_f32_32x32x16_bf16 v[0:15], v[40:43], v[184:187], v[0:15]
	v_exp_f32_e32 v120, v120
	v_exp_f32_e32 v121, v121
	v_exp_f32_e32 v122, v122
	v_exp_f32_e32 v123, v123
	v_mfma_f32_32x32x16_bf16 v[16:31], v[40:43], v[188:191], v[16:31]
	v_exp_f32_e32 v124, v124
	v_exp_f32_e32 v125, v125
	v_exp_f32_e32 v126, v126
	v_exp_f32_e32 v127, v127
	v_cvt_pk_bf16_f32 v44, v120, v121
	v_cvt_pk_bf16_f32 v45, v122, v123
	v_cvt_pk_bf16_f32 v46, v124, v125
	v_cvt_pk_bf16_f32 v47, v126, v127
	v_pk_add_f32 v[32:33], v[32:33], v[120:121]
	v_pk_add_f32 v[32:33], v[32:33], v[122:123]
	v_pk_add_f32 v[32:33], v[32:33], v[124:125]
	v_pk_add_f32 v[32:33], v[32:33], v[126:127]
	s_waitcnt lgkmcnt(4)
	v_mfma_f32_32x32x16_bf16 v[0:15], v[44:47], v[192:195], v[0:15]
	v_mfma_f32_32x32x16_bf16 v[16:31], v[44:47], v[196:199], v[16:31]
	s_waitcnt lgkmcnt(0)
	v_mfma_f32_32x32x16_bf16 v[96:111], v[80:83], v[136:139], v[64:79]
	ds_read_b64_tr_b16 v[168:169], v233 offset:8192
	ds_read_b64_tr_b16 v[170:171], v233 offset:9216
	ds_read_b64_tr_b16 v[172:173], v233 offset:8704
	ds_read_b64_tr_b16 v[174:175], v233 offset:9728
	v_mfma_f32_32x32x16_bf16 v[96:111], v[84:87], v[140:143], v[96:111]
	ds_read_b64_tr_b16 v[176:177], v233 offset:10240
	ds_read_b64_tr_b16 v[178:179], v233 offset:11264
	ds_read_b64_tr_b16 v[180:181], v233 offset:10752
	ds_read_b64_tr_b16 v[182:183], v233 offset:11776
	v_mfma_f32_32x32x16_bf16 v[112:127], v[88:91], v[136:139], v[64:79]
	ds_read_b64_tr_b16 v[184:185], v233 offset:12288
	ds_read_b64_tr_b16 v[186:187], v233 offset:13312
	ds_read_b64_tr_b16 v[188:189], v233 offset:12800
	ds_read_b64_tr_b16 v[190:191], v233 offset:13824
	v_mfma_f32_32x32x16_bf16 v[112:127], v[92:95], v[140:143], v[112:127]
	ds_read_b64_tr_b16 v[192:193], v233 offset:14336
	ds_read_b64_tr_b16 v[194:195], v233 offset:15360
	ds_read_b64_tr_b16 v[196:197], v233 offset:14848
	ds_read_b64_tr_b16 v[198:199], v233 offset:15872
	v_max3_f32 v34, v96, v97, v98
	v_max3_f32 v35, v99, v100, v101
	v_max3_f32 v34, v34, v102, v103
	v_max3_f32 v35, v35, v104, v105
	v_max3_f32 v34, v34, v106, v107
	v_max3_f32 v35, v35, v108, v109
	v_max3_f32 v34, v34, v110, v111
	s_nop 1
	v_max3_f32 v35, v35, v112, v113
	v_max3_f32 v34, v34, v114, v115
	v_max3_f32 v35, v35, v116, v117
	v_max3_f32 v34, v34, v118, v119
	v_max3_f32 v35, v35, v120, v121
	v_max3_f32 v34, v34, v122, v123
	v_max3_f32 v35, v35, v124, v125
	v_max3_f32 v34, v34, v126, v127
	v_max_f32_e32 v34, v34, v35
	v_mov_b32_e32 v35, v34
	s_nop 1
	v_permlane32_swap_b32_e32 v34, v35
	v_max_f32_e32 v34, v34, v35
	v_cmp_lt_f32_e32 vcc, s4, v34
	s_cbranch_vccnz .Lat_rare3
; #define LAS __attribute__((address_space(3)))
; __device__ __forceinline__ int crow(int r, int hi) { return (r & 3) + 8 * (r >> 2) + 4 * hi; }
; #define AT_LOAD(K0, K1, V0, V1, T) do { const size_t e_ = (size_t)(128 * (T) + sr) * 64 + sc; \
;         K0 = *(const bf16x8*)(kcp + e_); V0 = *(const bf16x8*)(vcp + e_); K1 = *(const bf16x8*)(kcp + e_ + 64 * 64); V1 = *(const bf16x8*)(vcp + e_ + 64 * 64); } while (0)
; #define AT_STORE(K0, K1, V0, V1, BUF) do { *(LAS bf16x8*)(lds + AT_K + (BUF) * AT_KB + kst0) = K0; *(LAS bf16x8*)(lds + AT_K + (BUF) * AT_KB + kst1) = K1; \
;         *(LAS bf16x8*)(lds + AT_V + (BUF) * AT_VB + vst0) = V0; *(LAS bf16x8*)(lds + AT_V + (BUF) * AT_VB + vst1) = V1; } while (0)
; template <int VAR>
; __device__ __forceinline__ void attn_unit(const Args& a, int l, int b, int h, int qrow0  , bool ctxu, const bf16* Z, bf16* Y, LAS unsigned char* lds) {
;     ...
;         AT_STORE(kb0, kb1, vb0_, vb1_, 1);
;         __syncthreads();
;         if (t + 3 < NT) AT_LOAD(kb0, kb1, vb0_, vb1_, t + 3);
;         attn_tile(Kb0 + AT_KB, vb0 + AT_VB, q0, q1, negm, m, o0, o1, lacc, false, wsf, r32, hi);
;         if (t + 2 < NT) AT_STORE(ka0, ka1, va0, va1, 0);
;     }
;     ...
;     float lam, omli;
;     { float s1 = 0.f, s2 = 0.f;
;       for (int i = 0; i < 32; ++i) { s1 += a.lam_q1[l * 32 + i] * a.lam_k1[l * 32 + i]; s2 += a.lam_q2[l * 32 + i] * a.lam_k2[l * 32 + i]; }
;       const float li = 0.8f - 0.6f * expf(-0.3f * (float)l); lam = expf(s1) - expf(s2) + li; omli = 1.f - li; }
;     LAS float* stg = (LAS float*)(lds + AT_ST) + wq * 2048;
;     if (comp == 1) {
; #pragma unroll
;         for (int r = 0; r < 16; ++r) { const int qr = crow(r, hi); const float il = lam * __builtin_amdgcn_rcpf(lacc[r]); stg[qr * 64 + r32] = o0[r] * il; stg[qr * 64 + 32 + r32] = o1[r] * il; }
;     }
;     __syncthreads();
;     if (comp == 0) {
; #pragma unroll
;         for (int r = 0; r < 16; ++r) { const int qr = crow(r, hi); const float il = __builtin_amdgcn_rcpf(lacc[r]); o0[r] = o0[r] * il - stg[qr * 64 + r32]; o1[r] = o1[r] * il - stg[qr * 64 + 32 + r32]; }
.Lat_back3:
	s_waitcnt vmcnt(4)
	ds_write_b128 v250, v[128:131] offset:0
	ds_write_b128 v250, v[144:147] offset:9216
	ds_write_b128 v251, v[132:135] offset:36864
	ds_write_b128 v229, v[148:151] offset:36864
	v_exp_f32_e32 v96, v96
	v_exp_f32_e32 v97, v97
	v_exp_f32_e32 v98, v98
	v_exp_f32_e32 v99, v99
	v_exp_f32_e32 v100, v100
	v_exp_f32_e32 v101, v101
	v_exp_f32_e32 v102, v102
	v_exp_f32_e32 v103, v103
	v_cvt_pk_bf16_f32 v40, v96, v97
	v_cvt_pk_bf16_f32 v41, v98, v99
	v_cvt_pk_bf16_f32 v42, v100, v101
	v_cvt_pk_bf16_f32 v43, v102, v103
	v_pk_add_f32 v[32:33], v[32:33], v[96:97]
	v_pk_add_f32 v[32:33], v[32:33], v[98:99]
	v_pk_add_f32 v[32:33], v[32:33], v[100:101]
	v_pk_add_f32 v[32:33], v[32:33], v[102:103]
	s_waitcnt lgkmcnt(15)
	v_mfma_f32_32x32x16_bf16 v[0:15], v[40:43], v[168:171], v[0:15]
	v_exp_f32_e32 v104, v104
	v_exp_f32_e32 v105, v105
	v_exp_f32_e32 v106, v106
	v_exp_f32_e32 v107, v107
	v_mfma_f32_32x32x16_bf16 v[16:31], v[40:43], v[172:175], v[16:31]
	v_exp_f32_e32 v108, v108
	v_exp_f32_e32 v109, v109
	v_exp_f32_e32 v110, v110
	v_exp_f32_e32 v111, v111
	v_cvt_pk_bf16_f32 v44, v104, v105
	v_cvt_pk_bf16_f32 v45, v106, v107
	v_cvt_pk_bf16_f32 v46, v108, v109
	v_cvt_pk_bf16_f32 v47, v110, v111
	v_pk_add_f32 v[32:33], v[32:33], v[104:105]
	v_pk_add_f32 v[32:33], v[32:33], v[106:107]
	v_pk_add_f32 v[32:33], v[32:33], v[108:109]
	v_pk_add_f32 v[32:33], v[32:33], v[110:111]
	s_waitcnt lgkmcnt(12)
	v_mfma_f32_32x32x16_bf16 v[0:15], v[44:47], v[176:179], v[0:15]
	v_exp_f32_e32 v112, v112
	v_exp_f32_e32 v113, v113
	v_exp_f32_e32 v114, v114
	v_exp_f32_e32 v115, v115
	v_mfma_f32_32x32x16_bf16 v[16:31], v[44:47], v[180:183], v[16:31]
	v_exp_f32_e32 v116, v116
	v_exp_f32_e32 v117, v117
	v_exp_f32_e32 v118, v118
	v_exp_f32_e32 v119, v119
	v_cvt_pk_bf16_f32 v40, v112, v113
	v_cvt_pk_bf16_f32 v41, v114, v115
	v_cvt_pk_bf16_f32 v42, v116, v117
	v_cvt_pk_bf16_f32 v43, v118, v119
	v_pk_add_f32 v[32:33], v[32:33], v[112:113]
	v_pk_add_f32 v[32:33], v[32:33], v[114:115]
	v_pk_add_f32 v[32:33], v[32:33], v[116:117]
	v_pk_add_f32 v[32:33], v[32:33], v[118:119]
	s_waitcnt lgkmcnt(0)
	s_barrier
	global_load_dwordx4 v[128:131], v200, s[36:37]
	global_load_dwordx4 v[132:135], v200, s[48:49]
	global_load_dwordx4 v[144:147], v201, s[36:37]
	global_load_dwordx4 v[148:151], v201, s[48:49]
	s_cmp_lt_u32 s93, 65
	s_cselect_b32 s50, 0x4000, 0
	s_add_u32 s36, s36, s50
	s_addc_u32 s37, s37, 0
	s_add_u32 s48, s48, s50
	s_addc_u32 s49, s49, 0
	s_add_u32 s93, s93, 1
	ds_read_b128 v[48:51], v235 offset:0
	ds_read_b128 v[52:55], v235 offset:32
	ds_read_b128 v[56:59], v235 offset:4608
	ds_read_b128 v[60:63], v235 offset:4640
	v_mfma_f32_32x32x16_bf16 v[0:15], v[40:43], v[184:187], v[0:15]
	v_exp_f32_e32 v120, v120
	v_exp_f32_e32 v121, v121
	v_exp_f32_e32 v122, v122
	v_exp_f32_e32 v123, v123
	v_mfma_f32_32x32x16_bf16 v[16:31], v[40:43], v[188:191], v[16:31]
	v_exp_f32_e32 v124, v124
	v_exp_f32_e32 v125, v125
	v_exp_f32_e32 v126, v126
	v_exp_f32_e32 v127, v127
	v_cvt_pk_bf16_f32 v44, v120, v121
	v_cvt_pk_bf16_f32 v45, v122, v123
	v_cvt_pk_bf16_f32 v46, v124, v125
	v_cvt_pk_bf16_f32 v47, v126, v127
	v_pk_add_f32 v[32:33], v[32:33], v[120:121]
	v_pk_add_f32 v[32:33], v[32:33], v[122:123]
	v_pk_add_f32 v[32:33], v[32:33], v[124:125]
	v_pk_add_f32 v[32:33], v[32:33], v[126:127]
	v_mfma_f32_32x32x16_bf16 v[0:15], v[44:47], v[192:195], v[0:15]
	v_mfma_f32_32x32x16_bf16 v[16:31], v[44:47], v[196:199], v[16:31]
	s_add_u32 s33, s33, 2
	s_cmp_lt_u32 s33, 66
	s_cbranch_scc1 .Lat_loop
	v_add_f32_e32 v34, v32, v33
	v_add_u32_e32 v36, s31, v216
	v_mov_b32_e32 v35, v34
	s_nop 1
	v_permlane32_swap_b32_e32 v34, v35
	v_add_f32_e32 v37, v34, v35
	s_waitcnt lgkmcnt(0)
	ds_write_b32 v232, v37
	s_waitcnt lgkmcnt(0)
	v_mov_b32_e32 v48, v36
	ds_read_b128 v[32:35], v48 offset:0
	ds_read_b128 v[36:39], v48 offset:32
	ds_read_b128 v[40:43], v48 offset:64
	ds_read_b128 v[44:47], v48 offset:96
	s_waitcnt vmcnt(0) lgkmcnt(0)
	s_branch .LBB0_459

; #define LAS __attribute__((address_space(3)))
; __device__ __forceinline__ int crow(int r, int hi) { return (r & 3) + 8 * (r >> 2) + 4 * hi; }
; template <int VAR>
; __device__ __forceinline__ void attn_unit(const Args& a, int l, int b, int h, int qrow0  , bool ctxu, const bf16* Z, bf16* Y, LAS unsigned char* lds) {
;     ...
;     float lam, omli;
;     { float s1 = 0.f, s2 = 0.f;
;       for (int i = 0; i < 32; ++i) { s1 += a.lam_q1[l * 32 + i] * a.lam_k1[l * 32 + i]; s2 += a.lam_q2[l * 32 + i] * a.lam_k2[l * 32 + i]; }
;       const float li = 0.8f - 0.6f * expf(-0.3f * (float)l); lam = expf(s1) - expf(s2) + li; omli = 1.f - li; }
;     LAS float* stg = (LAS float*)(lds + AT_ST) + wq * 2048;
;     if (comp == 1) {
; #pragma unroll
;         for (int r = 0; r < 16; ++r) { const int qr = crow(r, hi); const float il = lam * __builtin_amdgcn_rcpf(lacc[r]); stg[qr * 64 + r32] = o0[r] * il; stg[qr * 64 + 32 + r32] = o1[r] * il; }
;     }
.LBB0_459:
	s_lshl_b32 s9, s9, 13
	s_nop 5
	v_rcp_f32_e32 v68, v32
	v_rcp_f32_e32 v67, v33
	v_rcp_f32_e32 v66, v34
	v_rcp_f32_e32 v65, v35
	v_rcp_f32_e32 v64, v36
	v_rcp_f32_e32 v63, v37
	v_rcp_f32_e32 v62, v38
	v_rcp_f32_e32 v61, v39
	v_rcp_f32_e32 v60, v40
	v_rcp_f32_e32 v59, v41
	v_rcp_f32_e32 v58, v42
	v_rcp_f32_e32 v57, v43
	v_rcp_f32_e32 v56, v44
	v_rcp_f32_e32 v55, v45
	v_rcp_f32_e32 v54, v46
	v_rcp_f32_e32 v53, v47
	s_add_i32 s9, s9, 0
	s_add_i32 s9, s9, 0x11800
	v_lshlrev_b32_e32 v32, 10, v248
	v_lshlrev_b32_e32 v33, 2, v247
	s_cmp_eq_u32 s8, 1
	v_add3_u32 v52, s9, v32, v33
	s_cbranch_scc0 .LBB0_461
	v_add_u32_e32 v35, 0x800, v52
	v_mov_b32_e32 v32, v202
	v_mul_f32_e32 v33, v68, v32
	v_mul_f32_e32 v34, v0, v33
	v_mul_f32_e32 v33, v16, v33
	ds_write2_b32 v52, v34, v33 offset1:32
	v_mul_f32_e32 v33, v67, v32
	v_mul_f32_e32 v34, v1, v33
	v_mul_f32_e32 v33, v17, v33
	ds_write2_b32 v52, v34, v33 offset0:64 offset1:96
	v_mul_f32_e32 v33, v66, v32
	v_mul_f32_e32 v34, v2, v33
	v_mul_f32_e32 v33, v18, v33
	ds_write2_b32 v52, v34, v33 offset0:128 offset1:160
	v_mul_f32_e32 v33, v65, v32
	v_mul_f32_e32 v34, v3, v33
	v_mul_f32_e32 v33, v19, v33
	ds_write2_b32 v52, v34, v33 offset0:192 offset1:224
	v_mul_f32_e32 v33, v64, v32
	v_mul_f32_e32 v34, v4, v33
	v_mul_f32_e32 v33, v20, v33
	ds_write2_b32 v35, v34, v33 offset1:32
	v_mul_f32_e32 v33, v63, v32
	v_mul_f32_e32 v34, v5, v33
	v_mul_f32_e32 v33, v21, v33
	ds_write2_b32 v35, v34, v33 offset0:64 offset1:96
	v_mul_f32_e32 v33, v62, v32
	v_mul_f32_e32 v34, v6, v33
	v_mul_f32_e32 v33, v22, v33
	ds_write2_b32 v35, v34, v33 offset0:128 offset1:160
	v_mul_f32_e32 v33, v61, v32
	v_mul_f32_e32 v34, v7, v33
	v_mul_f32_e32 v33, v23, v33
	ds_write2_b32 v35, v34, v33 offset0:192 offset1:224
	v_mul_f32_e32 v33, v60, v32
	v_mul_f32_e32 v34, v8, v33
	v_mul_f32_e32 v33, v24, v33
	v_add_u32_e32 v35, 0x1000, v52
	ds_write2_b32 v35, v34, v33 offset1:32
	v_mul_f32_e32 v33, v59, v32
	v_mul_f32_e32 v34, v9, v33
	v_mul_f32_e32 v33, v25, v33
	ds_write2_b32 v35, v34, v33 offset0:64 offset1:96
	v_mul_f32_e32 v33, v58, v32
	v_mul_f32_e32 v34, v10, v33
	v_mul_f32_e32 v33, v26, v33
	ds_write2_b32 v35, v34, v33 offset0:128 offset1:160
	v_mul_f32_e32 v33, v57, v32
	v_mul_f32_e32 v34, v11, v33
	v_mul_f32_e32 v33, v27, v33
	ds_write2_b32 v35, v34, v33 offset0:192 offset1:224
	v_mul_f32_e32 v33, v56, v32
	v_mul_f32_e32 v34, v12, v33
	v_mul_f32_e32 v33, v28, v33
	v_add_u32_e32 v35, 0x1800, v52
	ds_write2_b32 v35, v34, v33 offset1:32
	v_mul_f32_e32 v33, v55, v32
	v_mul_f32_e32 v34, v13, v33
	v_mul_f32_e32 v33, v29, v33
	ds_write2_b32 v35, v34, v33 offset0:64 offset1:96
	v_mul_f32_e32 v33, v54, v32
	v_mul_f32_e32 v34, v14, v33
	v_mul_f32_e32 v33, v30, v33
	v_mul_f32_e32 v32, v53, v32
	ds_write2_b32 v35, v34, v33 offset0:128 offset1:160
	v_mul_f32_e32 v33, v15, v32
	v_mul_f32_e32 v32, v31, v32
	ds_write2_b32 v35, v33, v32 offset0:192 offset1:224
